# v96 + SwiGLU epilogues: rstd pre-multiplied by -log2(e) once per row, per-element -log2(e) multiply removed, sigmoid denominator K*(1+e) with K=log2(e)^2 via one fma (same formula, constants regrouped
# baseline (speedup 1.0000x reference)
; DI u32x2 pk4(f32x4 v) { u32x2 r; r.x = pk2(v[0], v[1]); r.y = pk2(v[2], v[3]); return r; }
; #define ROWS8 _Pragma("unroll") for (int ai = 0; ai < 2; ++ai) _Pragma("unroll") for (int m = 0; m < 4; ++m) if (ai == 0 || !hf)
; #define LOAD_ROW_RS(rsv, ssqp, invn) float rsv[2][4]; ROWS8_ALL rsv[ai][m] = (ssqp)[row0 + ai * HALF + m * 16]; ROWS8_ALL rsv[ai][m] = rstd_of(rsv[ai][m], invn)
; DI float silu_f(float x) { return x * __builtin_amdgcn_rcpf(1.f + __builtin_amdgcn_exp2f(-1.4426950409f * x)); }
; DI float rstd_of(float ssq, float inv_n) { return __builtin_amdgcn_rsqf(ssq * inv_n + 1e-6f); }
;     DI void operator()(const Acc& acc, const Unit& u, int wr, int wc, int fr, int fq) const {
;     ...
;             LOAD_ROW_RS(rsv, SSQ(PH == 5 ? 2 : 6), 1.f / 2048.f);
;             const int ac0 = u.pn * 128 + wc * 32 + 8 * fq;
;             ROWS8 { const int r = row0 + ai * HALF + m * 16; const float rs = rsv[ai][m];
;                 u32x4 w;
; #pragma unroll
;                 for (int bj = 0; bj < 2; ++bj) { const f32x4 g = acc[ai][bj][m][0] * rs, uu = acc[ai][bj][m][1] * rs;
;                     f32x4 a; a[0] = silu_f(g[0]) * uu[0]; a[1] = silu_f(g[1]) * uu[1]; a[2] = silu_f(g[2]) * uu[2]; a[3] = silu_f(g[3]) * uu[3];
;                     const u32x2 h = pk4(a); if (bj == 0) { w.x = h.x; w.y = h.y; } else { w.z = h.x; w.w = h.y; } }
;                 *(u32x4*)(WSB(OFF_ACT) + (size_t)r * DFF + ac0) = w;
;             }
.Lpeel_2_exit:
	s_mov_b32 s99, 0x40053526
	v_lshl_add_u32 v142, s22, 8, v155
	v_or_b32_e32 v156, 16, v142
	v_ashrrev_i32_e32 v157, 31, v156
	v_or_b32_e32 v152, 32, v142
	v_or_b32_e32 v150, 48, v142
	v_lshl_add_u64 v[138:139], v[156:157], 2, s[10:11]
	v_ashrrev_i32_e32 v153, 31, v152
	v_ashrrev_i32_e32 v151, 31, v150
	v_ashrrev_i32_e32 v143, 31, v142
	v_lshl_add_u64 v[140:141], v[152:153], 2, s[10:11]
	v_lshl_add_u64 v[144:145], v[150:151], 2, s[10:11]
	v_lshl_add_u64 v[146:147], v[142:143], 2, s[10:11]
	v_add_u32_e32 v148, 0x80, v142
	v_add_u32_e32 v146, 0x90, v142
	v_add_u32_e32 v144, 0xa0, v142
	v_add_u32_e32 v138, 0xb0, v142
	v_ashrrev_i32_e32 v149, 31, v148
	v_ashrrev_i32_e32 v147, 31, v146
	v_ashrrev_i32_e32 v145, 31, v144
	v_ashrrev_i32_e32 v139, 31, v138
	v_lshl_add_u64 v[140:141], v[148:149], 2, s[10:11]
	v_lshl_add_u64 v[164:165], v[146:147], 2, s[10:11]
	v_lshl_add_u64 v[166:167], v[144:145], 2, s[10:11]
	v_lshl_add_u64 v[168:169], v[138:139], 2, s[10:11]
	v_lshl_add_u32 v164, s56, 7, v159
	v_mov_b64_e32 v[140:141], s[12:13]
	v_ashrrev_i32_e32 v165, 31, v164
	v_mad_i64_i32 v[166:167], s[24:25], v142, s55, v[140:141]
	v_lshlrev_b64 v[142:143], 1, v[164:165]
	v_lshl_add_u64 v[164:165], v[166:167], 0, v[142:143]
	s_and_b64 vcc, exec, s[2:3]
	s_mov_b32 s56, s14
	s_mov_b32 s22, s16
	s_mov_b64 s[30:31], s[18:19]
	s_mov_b64 s[28:29], s[20:21]
	v_mov_b32_e32 v151, v221
	v_mov_b32_e32 v153, v222
	v_mov_b32_e32 v154, v223
	v_mov_b32_e32 v157, v220
	v_mov_b32_e32 v139, v224
	v_mov_b32_e32 v145, v225
	v_mov_b32_e32 v147, v226
	v_mov_b32_e32 v149, v227
	v_fmamk_f32 v151, v151, 0x3a000000, v163
	v_rsq_f32_e32 v168, v151
	s_nop 0
	v_mul_f32_e32 v168, 0xbfb8aa3b, v168
	v_fmamk_f32 v153, v153, 0x3a000000, v163
	v_fmamk_f32 v157, v157, 0x3a000000, v163
	v_rsq_f32_e32 v166, v157
	s_nop 0
	v_mul_f32_e32 v166, 0xbfb8aa3b, v166
	v_rsq_f32_e32 v170, v153
	s_nop 0
	v_mul_f32_e32 v170, 0xbfb8aa3b, v170
	v_pk_mul_f32 v[118:119], v[118:119], v[168:169] op_sel_hi:[1,0]
	v_pk_mul_f32 v[116:117], v[116:117], v[168:169] op_sel_hi:[1,0]
	v_pk_mul_f32 v[126:127], v[126:127], v[166:167] op_sel_hi:[1,0]
	v_pk_mul_f32 v[124:125], v[124:125], v[166:167] op_sel_hi:[1,0]
	v_pk_mul_f32 v[114:115], v[114:115], v[166:167] op_sel_hi:[1,0]
	v_pk_mul_f32 v[112:113], v[112:113], v[166:167] op_sel_hi:[1,0]
	v_pk_mul_f32 v[122:123], v[122:123], v[166:167] op_sel_hi:[1,0]
	v_pk_mul_f32 v[120:121], v[120:121], v[166:167] op_sel_hi:[1,0]
	v_pk_mul_f32 v[110:111], v[110:111], v[166:167] op_sel_hi:[1,0]
	v_pk_mul_f32 v[108:109], v[108:109], v[166:167] op_sel_hi:[1,0]
	v_exp_f32_e32 v151, v124
	v_exp_f32_e32 v153, v125
	v_exp_f32_e32 v157, v126
	v_exp_f32_e32 v166, v127
	v_exp_f32_e32 v167, v112
	v_exp_f32_e32 v169, v113
	v_exp_f32_e32 v171, v114
	v_exp_f32_e32 v172, v115
	v_exp_f32_e32 v178, v116
	v_fma_f32 v151, v151, s99, s99
	v_fma_f32 v153, v153, s99, s99
	v_fma_f32 v157, v157, s99, s99
	v_fma_f32 v173, v166, s99, s99
	v_fma_f32 v174, v167, s99, s99
	v_fma_f32 v169, v169, s99, s99
	v_fma_f32 v171, v171, s99, s99
	v_fma_f32 v177, v172, s99, s99
	v_rcp_f32_e32 v166, v151
	v_rcp_f32_e32 v167, v153
	v_rcp_f32_e32 v172, v157
	v_rcp_f32_e32 v173, v173
	v_rcp_f32_e32 v174, v174
	v_rcp_f32_e32 v175, v169
	v_rcp_f32_e32 v176, v171
	v_rcp_f32_e32 v177, v177
	v_pk_mul_f32 v[124:125], v[124:125], v[166:167]
	v_pk_mul_f32 v[126:127], v[126:127], v[172:173]
	v_pk_mul_f32 v[112:113], v[112:113], v[174:175]
	v_pk_mul_f32 v[114:115], v[114:115], v[176:177]
	v_pk_mul_f32 v[120:121], v[120:121], v[124:125]
	v_pk_mul_f32 v[122:123], v[122:123], v[126:127]
	v_pk_mul_f32 v[112:113], v[108:109], v[112:113]
	v_pk_mul_f32 v[114:115], v[110:111], v[114:115]
	v_cvt_pk_bf16_f32 v108, v120, v121
	v_cvt_pk_bf16_f32 v109, v122, v123
	v_cvt_pk_bf16_f32 v110, v112, v113
	v_cvt_pk_bf16_f32 v111, v114, v115
	global_store_dwordx4 v[164:165], v[108:111], off
	v_pk_mul_f32 v[104:105], v[104:105], v[168:169] op_sel_hi:[1,0]
	v_pk_mul_f32 v[106:107], v[106:107], v[168:169] op_sel_hi:[1,0]
	v_exp_f32_e32 v109, v117
	v_exp_f32_e32 v110, v118
	v_exp_f32_e32 v111, v119
	v_fma_f32 v108, v178, s99, s99
	v_fma_f32 v109, v109, s99, s99
	v_rcp_f32_e32 v108, v108
	v_rcp_f32_e32 v109, v109
	v_fma_f32 v110, v110, s99, s99
	v_fma_f32 v111, v111, s99, s99
	v_rcp_f32_e32 v110, v110
	v_rcp_f32_e32 v111, v111
	v_pk_mul_f32 v[108:109], v[116:117], v[108:109]
	v_pk_mul_f32 v[100:101], v[100:101], v[168:169] op_sel_hi:[1,0]
	v_pk_mul_f32 v[104:105], v[104:105], v[108:109]
	v_pk_mul_f32 v[108:109], v[118:119], v[110:111]
	v_cvt_pk_bf16_f32 v104, v104, v105
	v_pk_mul_f32 v[106:107], v[106:107], v[108:109]
	v_pk_mul_f32 v[102:103], v[102:103], v[168:169] op_sel_hi:[1,0]
	v_cvt_pk_bf16_f32 v105, v106, v107
	v_exp_f32_e32 v106, v100
	v_exp_f32_e32 v107, v101
	v_exp_f32_e32 v108, v102
	v_exp_f32_e32 v109, v103
	v_fma_f32 v106, v106, s99, s99
	v_fma_f32 v107, v107, s99, s99
	v_rcp_f32_e32 v106, v106
	v_rcp_f32_e32 v107, v107
	v_fma_f32 v108, v108, s99, s99
	v_fma_f32 v109, v109, s99, s99
	v_rcp_f32_e32 v108, v108
	v_rcp_f32_e32 v109, v109
	v_pk_mul_f32 v[92:93], v[92:93], v[168:169] op_sel_hi:[1,0]
	v_pk_mul_f32 v[100:101], v[100:101], v[106:107]
	v_pk_mul_f32 v[94:95], v[94:95], v[168:169] op_sel_hi:[1,0]
	v_pk_mul_f32 v[92:93], v[92:93], v[100:101]
	v_pk_mul_f32 v[100:101], v[102:103], v[108:109]
	v_cvt_pk_bf16_f32 v106, v92, v93
	v_pk_mul_f32 v[94:95], v[94:95], v[100:101]
	v_mad_i64_i32 v[92:93], s[24:25], v156, s55, v[140:141]
	v_cvt_pk_bf16_f32 v107, v94, v95
	v_lshl_add_u64 v[92:93], v[92:93], 0, v[142:143]
	global_store_dwordx4 v[92:93], v[104:107], off
	v_pk_mul_f32 v[92:93], v[98:99], v[170:171] op_sel_hi:[1,0]
; DI u32x2 pk4(f32x4 v) { u32x2 r; r.x = pk2(v[0], v[1]); r.y = pk2(v[2], v[3]); return r; }
; #define ROWS8 _Pragma("unroll") for (int ai = 0; ai < 2; ++ai) _Pragma("unroll") for (int m = 0; m < 4; ++m) if (ai == 0 || !hf)
; #define LOAD_ROW_RS(rsv, ssqp, invn) float rsv[2][4]; ROWS8_ALL rsv[ai][m] = (ssqp)[row0 + ai * HALF + m * 16]; ROWS8_ALL rsv[ai][m] = rstd_of(rsv[ai][m], invn)
; DI float silu_f(float x) { return x * __builtin_amdgcn_rcpf(1.f + __builtin_amdgcn_exp2f(-1.4426950409f * x)); }
; DI float rstd_of(float ssq, float inv_n) { return __builtin_amdgcn_rsqf(ssq * inv_n + 1e-6f); }
;     DI void operator()(const Acc& acc, const Unit& u, int wr, int wc, int fr, int fq) const {
;     ...
;             LOAD_ROW_RS(rsv, SSQ(PH == 5 ? 2 : 6), 1.f / 2048.f);
;             const int ac0 = u.pn * 128 + wc * 32 + 8 * fq;
;             ROWS8 { const int r = row0 + ai * HALF + m * 16; const float rs = rsv[ai][m];
;                 u32x4 w;
; #pragma unroll
;                 for (int bj = 0; bj < 2; ++bj) { const f32x4 g = acc[ai][bj][m][0] * rs, uu = acc[ai][bj][m][1] * rs;
;                     f32x4 a; a[0] = silu_f(g[0]) * uu[0]; a[1] = silu_f(g[1]) * uu[1]; a[2] = silu_f(g[2]) * uu[2]; a[3] = silu_f(g[3]) * uu[3];
;                     const u32x2 h = pk4(a); if (bj == 0) { w.x = h.x; w.y = h.y; } else { w.z = h.x; w.w = h.y; } }
;                 *(u32x4*)(WSB(OFF_ACT) + (size_t)r * DFF + ac0) = w;
;             }
	v_pk_mul_f32 v[94:95], v[96:97], v[170:171] op_sel_hi:[1,0]
	v_exp_f32_e32 v96, v94
	v_exp_f32_e32 v97, v95
	v_exp_f32_e32 v98, v92
	v_exp_f32_e32 v99, v93
	v_fma_f32 v96, v96, s99, s99
	v_fma_f32 v97, v97, s99, s99
	v_fma_f32 v98, v98, s99, s99
	v_fma_f32 v99, v99, s99, s99
	v_rcp_f32_e32 v96, v96
	v_rcp_f32_e32 v97, v97
	v_rcp_f32_e32 v98, v98
	v_rcp_f32_e32 v99, v99
	v_pk_mul_f32 v[90:91], v[90:91], v[170:171] op_sel_hi:[1,0]
	v_pk_mul_f32 v[88:89], v[88:89], v[170:171] op_sel_hi:[1,0]
	v_pk_mul_f32 v[94:95], v[94:95], v[96:97]
	v_pk_mul_f32 v[92:93], v[92:93], v[98:99]
	v_pk_mul_f32 v[88:89], v[88:89], v[94:95]
	v_pk_mul_f32 v[90:91], v[90:91], v[92:93]
	v_pk_mul_f32 v[84:85], v[84:85], v[170:171] op_sel_hi:[1,0]
	v_cvt_pk_bf16_f32 v88, v88, v89
	v_cvt_pk_bf16_f32 v89, v90, v91
	v_pk_mul_f32 v[86:87], v[86:87], v[170:171] op_sel_hi:[1,0]
	v_exp_f32_e32 v90, v84
	v_exp_f32_e32 v91, v85
	v_exp_f32_e32 v92, v86
	v_exp_f32_e32 v93, v87
	v_fma_f32 v90, v90, s99, s99
	v_fma_f32 v91, v91, s99, s99
	v_rcp_f32_e32 v90, v90
	v_rcp_f32_e32 v91, v91
	v_fma_f32 v92, v92, s99, s99
	v_fma_f32 v93, v93, s99, s99
	v_rcp_f32_e32 v92, v92
	v_rcp_f32_e32 v93, v93
	v_fmamk_f32 v154, v154, 0x3a000000, v163
	v_rsq_f32_e32 v154, v154
	s_nop 0
	v_mul_f32_e32 v154, 0xbfb8aa3b, v154
	v_pk_mul_f32 v[76:77], v[76:77], v[170:171] op_sel_hi:[1,0]
	v_pk_mul_f32 v[84:85], v[84:85], v[90:91]
	v_pk_mul_f32 v[78:79], v[78:79], v[170:171] op_sel_hi:[1,0]
	v_pk_mul_f32 v[76:77], v[76:77], v[84:85]
	v_pk_mul_f32 v[84:85], v[86:87], v[92:93]
	v_cvt_pk_bf16_f32 v90, v76, v77
	v_pk_mul_f32 v[78:79], v[78:79], v[84:85]
	v_mad_i64_i32 v[76:77], s[24:25], v152, s55, v[140:141]
	v_cvt_pk_bf16_f32 v91, v78, v79
	v_lshl_add_u64 v[76:77], v[76:77], 0, v[142:143]
	global_store_dwordx4 v[76:77], v[88:91], off
	v_pk_mul_f32 v[76:77], v[82:83], v[154:155] op_sel_hi:[1,0]
	v_pk_mul_f32 v[78:79], v[80:81], v[154:155] op_sel_hi:[1,0]
	v_exp_f32_e32 v80, v78
	v_exp_f32_e32 v81, v79
	v_exp_f32_e32 v82, v76
	v_exp_f32_e32 v83, v77
	v_fma_f32 v80, v80, s99, s99
	v_fma_f32 v81, v81, s99, s99
	v_fma_f32 v82, v82, s99, s99
	v_fma_f32 v83, v83, s99, s99
	v_rcp_f32_e32 v80, v80
	v_rcp_f32_e32 v81, v81
	v_rcp_f32_e32 v82, v82
	v_rcp_f32_e32 v83, v83
	v_pk_mul_f32 v[74:75], v[74:75], v[154:155] op_sel_hi:[1,0]
	v_pk_mul_f32 v[72:73], v[72:73], v[154:155] op_sel_hi:[1,0]
	v_pk_mul_f32 v[78:79], v[78:79], v[80:81]
	v_pk_mul_f32 v[76:77], v[76:77], v[82:83]
	v_pk_mul_f32 v[72:73], v[72:73], v[78:79]
	v_pk_mul_f32 v[74:75], v[74:75], v[76:77]
	v_pk_mul_f32 v[68:69], v[68:69], v[154:155] op_sel_hi:[1,0]
	v_cvt_pk_bf16_f32 v72, v72, v73
	v_cvt_pk_bf16_f32 v73, v74, v75
	v_pk_mul_f32 v[70:71], v[70:71], v[154:155] op_sel_hi:[1,0]
	v_exp_f32_e32 v74, v68
	v_exp_f32_e32 v75, v69
	v_exp_f32_e32 v76, v70
	v_exp_f32_e32 v77, v71
	v_fma_f32 v74, v74, s99, s99
	v_fma_f32 v75, v75, s99, s99
	v_rcp_f32_e32 v74, v74
	v_rcp_f32_e32 v75, v75
	v_fma_f32 v76, v76, s99, s99
	v_fma_f32 v77, v77, s99, s99
	v_rcp_f32_e32 v76, v76
	v_rcp_f32_e32 v77, v77
	v_pk_mul_f32 v[64:65], v[64:65], v[154:155] op_sel_hi:[1,0]
	v_pk_mul_f32 v[68:69], v[68:69], v[74:75]
	v_pk_mul_f32 v[66:67], v[66:67], v[154:155] op_sel_hi:[1,0]
	v_pk_mul_f32 v[64:65], v[64:65], v[68:69]
	v_pk_mul_f32 v[68:69], v[70:71], v[76:77]
	v_cvt_pk_bf16_f32 v74, v64, v65
	v_pk_mul_f32 v[66:67], v[66:67], v[68:69]
	v_mad_i64_i32 v[64:65], s[24:25], v150, s55, v[140:141]
	v_cvt_pk_bf16_f32 v75, v66, v67
	v_fmamk_f32 v66, v139, 0x3a000000, v163
	v_rsq_f32_e32 v68, v66
	s_nop 0
	v_mul_f32_e32 v68, 0xbfb8aa3b, v68
	v_lshl_add_u64 v[64:65], v[64:65], 0, v[142:143]
	global_store_dwordx4 v[64:65], v[72:75], off
	v_fmamk_f32 v65, v147, 0x3a000000, v163
	v_rsq_f32_e32 v66, v65
	s_nop 0
	v_mul_f32_e32 v66, 0xbfb8aa3b, v66
	v_fmamk_f32 v65, v145, 0x3a000000, v163
	v_pk_mul_f32 v[60:61], v[60:61], v[68:69] op_sel_hi:[1,0]
	v_rsq_f32_e32 v70, v65
	s_nop 0
	v_mul_f32_e32 v70, 0xbfb8aa3b, v70
	v_exp_f32_e32 v65, v60
	v_exp_f32_e32 v67, v61
	v_pk_mul_f32 v[62:63], v[62:63], v[68:69] op_sel_hi:[1,0]
	v_fma_f32 v65, v65, s99, s99
	v_rcp_f32_e32 v72, v65
	v_fma_f32 v65, v67, s99, s99
	v_pk_mul_f32 v[58:59], v[58:59], v[68:69] op_sel_hi:[1,0]
	v_exp_f32_e32 v67, v62
	v_exp_f32_e32 v69, v63
	v_rcp_f32_e32 v73, v65
	v_fma_f32 v65, v67, s99, s99
	v_rcp_f32_e32 v74, v65
	v_fma_f32 v65, v69, s99, s99
	v_rcp_f32_e32 v75, v65
	v_pk_mul_f32 v[56:57], v[56:57], v[68:69] op_sel_hi:[1,0]
	v_pk_mul_f32 v[60:61], v[60:61], v[72:73]
	v_pk_mul_f32 v[52:53], v[52:53], v[68:69] op_sel_hi:[1,0]
	v_pk_mul_f32 v[56:57], v[56:57], v[60:61]
	v_pk_mul_f32 v[60:61], v[62:63], v[74:75]
	v_cvt_pk_bf16_f32 v56, v56, v57
	v_pk_mul_f32 v[58:59], v[58:59], v[60:61]
	v_pk_mul_f32 v[54:55], v[54:55], v[68:69] op_sel_hi:[1,0]
	v_cvt_pk_bf16_f32 v57, v58, v59
	v_exp_f32_e32 v58, v52
	v_exp_f32_e32 v59, v53
	v_exp_f32_e32 v60, v54
	v_exp_f32_e32 v61, v55
	v_fma_f32 v58, v58, s99, s99
	v_fma_f32 v59, v59, s99, s99
	v_rcp_f32_e32 v58, v58
	v_rcp_f32_e32 v59, v59
	v_fma_f32 v60, v60, s99, s99
	v_fma_f32 v61, v61, s99, s99
	v_rcp_f32_e32 v60, v60
	v_rcp_f32_e32 v61, v61
	v_pk_mul_f32 v[44:45], v[44:45], v[68:69] op_sel_hi:[1,0]
	v_pk_mul_f32 v[52:53], v[52:53], v[58:59]
	v_pk_mul_f32 v[46:47], v[46:47], v[68:69] op_sel_hi:[1,0]
	v_pk_mul_f32 v[44:45], v[44:45], v[52:53]
	v_pk_mul_f32 v[52:53], v[54:55], v[60:61]
	v_cvt_pk_bf16_f32 v58, v44, v45
	v_pk_mul_f32 v[46:47], v[46:47], v[52:53]
	v_mad_i64_i32 v[44:45], s[24:25], v148, s55, v[140:141]
; DI u32x2 pk4(f32x4 v) { u32x2 r; r.x = pk2(v[0], v[1]); r.y = pk2(v[2], v[3]); return r; }
; #define ROWS8 _Pragma("unroll") for (int ai = 0; ai < 2; ++ai) _Pragma("unroll") for (int m = 0; m < 4; ++m) if (ai == 0 || !hf)
; DI float silu_f(float x) { return x * __builtin_amdgcn_rcpf(1.f + __builtin_amdgcn_exp2f(-1.4426950409f * x)); }
;     DI void operator()(const Acc& acc, const Unit& u, int wr, int wc, int fr, int fq) const {
;     ...
;             ROWS8 { const int r = row0 + ai * HALF + m * 16; const float rs = rsv[ai][m];
;                 u32x4 w;
; #pragma unroll
;                 for (int bj = 0; bj < 2; ++bj) { const f32x4 g = acc[ai][bj][m][0] * rs, uu = acc[ai][bj][m][1] * rs;
;                     f32x4 a; a[0] = silu_f(g[0]) * uu[0]; a[1] = silu_f(g[1]) * uu[1]; a[2] = silu_f(g[2]) * uu[2]; a[3] = silu_f(g[3]) * uu[3];
;                     const u32x2 h = pk4(a); if (bj == 0) { w.x = h.x; w.y = h.y; } else { w.z = h.x; w.w = h.y; } }
;                 *(u32x4*)(WSB(OFF_ACT) + (size_t)r * DFF + ac0) = w;
	v_cvt_pk_bf16_f32 v59, v46, v47
	v_lshl_add_u64 v[44:45], v[44:45], 0, v[142:143]
	global_store_dwordx4 v[44:45], v[56:59], off
	v_pk_mul_f32 v[44:45], v[50:51], v[70:71] op_sel_hi:[1,0]
	v_pk_mul_f32 v[46:47], v[48:49], v[70:71] op_sel_hi:[1,0]
	v_exp_f32_e32 v48, v46
	v_exp_f32_e32 v49, v47
	v_exp_f32_e32 v50, v44
	v_exp_f32_e32 v51, v45
	v_fma_f32 v48, v48, s99, s99
	v_fma_f32 v49, v49, s99, s99
	v_fma_f32 v50, v50, s99, s99
	v_fma_f32 v51, v51, s99, s99
	v_rcp_f32_e32 v48, v48
	v_rcp_f32_e32 v49, v49
	v_rcp_f32_e32 v50, v50
	v_rcp_f32_e32 v51, v51
	v_pk_mul_f32 v[42:43], v[42:43], v[70:71] op_sel_hi:[1,0]
	v_pk_mul_f32 v[40:41], v[40:41], v[70:71] op_sel_hi:[1,0]
	v_pk_mul_f32 v[46:47], v[46:47], v[48:49]
	v_pk_mul_f32 v[44:45], v[44:45], v[50:51]
	v_pk_mul_f32 v[40:41], v[40:41], v[46:47]
	v_pk_mul_f32 v[42:43], v[42:43], v[44:45]
	v_pk_mul_f32 v[36:37], v[36:37], v[70:71] op_sel_hi:[1,0]
	v_cvt_pk_bf16_f32 v40, v40, v41
	v_cvt_pk_bf16_f32 v41, v42, v43
	v_pk_mul_f32 v[38:39], v[38:39], v[70:71] op_sel_hi:[1,0]
	v_exp_f32_e32 v42, v36
	v_exp_f32_e32 v43, v37
	v_exp_f32_e32 v44, v38
	v_exp_f32_e32 v45, v39
	v_fma_f32 v42, v42, s99, s99
	v_fma_f32 v43, v43, s99, s99
	v_rcp_f32_e32 v42, v42
	v_rcp_f32_e32 v43, v43
	v_fma_f32 v44, v44, s99, s99
	v_fma_f32 v45, v45, s99, s99
	v_rcp_f32_e32 v44, v44
	v_rcp_f32_e32 v45, v45
	v_pk_mul_f32 v[28:29], v[28:29], v[70:71] op_sel_hi:[1,0]
	v_pk_mul_f32 v[36:37], v[36:37], v[42:43]
	v_pk_mul_f32 v[30:31], v[30:31], v[70:71] op_sel_hi:[1,0]
	v_pk_mul_f32 v[28:29], v[28:29], v[36:37]
	v_pk_mul_f32 v[36:37], v[38:39], v[44:45]
	v_cvt_pk_bf16_f32 v42, v28, v29
	v_pk_mul_f32 v[30:31], v[30:31], v[36:37]
	v_mad_i64_i32 v[28:29], s[24:25], v146, s55, v[140:141]
	v_cvt_pk_bf16_f32 v43, v30, v31
	v_lshl_add_u64 v[28:29], v[28:29], 0, v[142:143]
	global_store_dwordx4 v[28:29], v[40:43], off
	v_pk_mul_f32 v[28:29], v[34:35], v[66:67] op_sel_hi:[1,0]
	v_pk_mul_f32 v[30:31], v[32:33], v[66:67] op_sel_hi:[1,0]
	v_exp_f32_e32 v32, v30
	v_exp_f32_e32 v33, v31
	v_exp_f32_e32 v34, v28
	v_exp_f32_e32 v35, v29
	v_fma_f32 v32, v32, s99, s99
	v_fma_f32 v33, v33, s99, s99
	v_fma_f32 v34, v34, s99, s99
	v_fma_f32 v35, v35, s99, s99
	v_rcp_f32_e32 v32, v32
	v_rcp_f32_e32 v33, v33
	v_rcp_f32_e32 v34, v34
	v_rcp_f32_e32 v35, v35
	v_pk_mul_f32 v[26:27], v[26:27], v[66:67] op_sel_hi:[1,0]
	v_pk_mul_f32 v[24:25], v[24:25], v[66:67] op_sel_hi:[1,0]
	v_pk_mul_f32 v[30:31], v[30:31], v[32:33]
	v_pk_mul_f32 v[28:29], v[28:29], v[34:35]
	v_pk_mul_f32 v[24:25], v[24:25], v[30:31]
	v_pk_mul_f32 v[26:27], v[26:27], v[28:29]
	v_pk_mul_f32 v[20:21], v[20:21], v[66:67] op_sel_hi:[1,0]
	v_cvt_pk_bf16_f32 v24, v24, v25
	v_cvt_pk_bf16_f32 v25, v26, v27
	v_pk_mul_f32 v[22:23], v[22:23], v[66:67] op_sel_hi:[1,0]
	v_exp_f32_e32 v26, v20
	v_exp_f32_e32 v27, v21
	v_exp_f32_e32 v28, v22
	v_exp_f32_e32 v29, v23
	v_fma_f32 v26, v26, s99, s99
	v_fma_f32 v27, v27, s99, s99
	v_rcp_f32_e32 v26, v26
	v_rcp_f32_e32 v27, v27
	v_fma_f32 v28, v28, s99, s99
	v_fma_f32 v29, v29, s99, s99
	v_rcp_f32_e32 v28, v28
	v_rcp_f32_e32 v29, v29
	v_fmamk_f32 v64, v149, 0x3a000000, v163
	v_rsq_f32_e32 v64, v64
	s_nop 0
	v_mul_f32_e32 v64, 0xbfb8aa3b, v64
	v_pk_mul_f32 v[12:13], v[12:13], v[66:67] op_sel_hi:[1,0]
	v_pk_mul_f32 v[20:21], v[20:21], v[26:27]
	v_pk_mul_f32 v[14:15], v[14:15], v[66:67] op_sel_hi:[1,0]
	v_pk_mul_f32 v[12:13], v[12:13], v[20:21]
	v_pk_mul_f32 v[20:21], v[22:23], v[28:29]
	v_cvt_pk_bf16_f32 v26, v12, v13
	v_pk_mul_f32 v[14:15], v[14:15], v[20:21]
	v_mad_i64_i32 v[12:13], s[24:25], v144, s55, v[140:141]
	v_cvt_pk_bf16_f32 v27, v14, v15
	v_lshl_add_u64 v[12:13], v[12:13], 0, v[142:143]
	global_store_dwordx4 v[12:13], v[24:27], off
	v_pk_mul_f32 v[12:13], v[18:19], v[64:65] op_sel_hi:[1,0]
	v_pk_mul_f32 v[14:15], v[16:17], v[64:65] op_sel_hi:[1,0]
	v_exp_f32_e32 v16, v14
	v_exp_f32_e32 v17, v15
	v_exp_f32_e32 v18, v12
	v_exp_f32_e32 v19, v13
	v_fma_f32 v16, v16, s99, s99
	v_fma_f32 v17, v17, s99, s99
	v_fma_f32 v18, v18, s99, s99
	v_fma_f32 v19, v19, s99, s99
	v_rcp_f32_e32 v16, v16
	v_rcp_f32_e32 v17, v17
	v_rcp_f32_e32 v18, v18
	v_rcp_f32_e32 v19, v19
	v_pk_mul_f32 v[10:11], v[10:11], v[64:65] op_sel_hi:[1,0]
	v_pk_mul_f32 v[8:9], v[8:9], v[64:65] op_sel_hi:[1,0]
	v_pk_mul_f32 v[14:15], v[14:15], v[16:17]
	v_pk_mul_f32 v[12:13], v[12:13], v[18:19]
	v_pk_mul_f32 v[8:9], v[8:9], v[14:15]
	v_pk_mul_f32 v[10:11], v[10:11], v[12:13]
	v_pk_mul_f32 v[4:5], v[4:5], v[64:65] op_sel_hi:[1,0]
	v_cvt_pk_bf16_f32 v8, v8, v9
	v_cvt_pk_bf16_f32 v9, v10, v11
	v_pk_mul_f32 v[6:7], v[6:7], v[64:65] op_sel_hi:[1,0]
	v_exp_f32_e32 v10, v4
	v_exp_f32_e32 v11, v5
	v_exp_f32_e32 v12, v6
	v_exp_f32_e32 v13, v7
	v_fma_f32 v10, v10, s99, s99
	v_fma_f32 v11, v11, s99, s99
	v_rcp_f32_e32 v10, v10
	v_rcp_f32_e32 v11, v11
	v_fma_f32 v12, v12, s99, s99
	v_fma_f32 v13, v13, s99, s99
	v_rcp_f32_e32 v12, v12
	v_rcp_f32_e32 v13, v13
	v_pk_mul_f32 v[0:1], v[0:1], v[64:65] op_sel_hi:[1,0]
	v_pk_mul_f32 v[4:5], v[4:5], v[10:11]
	v_pk_mul_f32 v[2:3], v[2:3], v[64:65] op_sel_hi:[1,0]
	v_pk_mul_f32 v[0:1], v[0:1], v[4:5]
	v_pk_mul_f32 v[4:5], v[6:7], v[12:13]
	v_cvt_pk_bf16_f32 v10, v0, v1
	v_pk_mul_f32 v[2:3], v[2:3], v[4:5]
	v_mad_i64_i32 v[0:1], s[24:25], v138, s55, v[140:141]
	v_cvt_pk_bf16_f32 v11, v2, v3
	v_lshl_add_u64 v[0:1], v[0:1], 0, v[142:143]
	global_store_dwordx4 v[0:1], v[8:11], off
	s_cbranch_vccz .LBB0_702
	s_waitcnt vmcnt(0)
	s_cmpk_gt_u32 s88, 0xff
	s_cbranch_scc1 .LBB0_709
	s_barrier
